# metafuse + ssm1deep: SSM pass-1 step loop with 4 u fragments in flight (4x unrolled)
# baseline (speedup 1.0000x reference)
; __device__ __forceinline__ f32x2 pk_fma(f32x2 a, f32x2 b, f32x2 c) { return __builtin_elementwise_fma(a, b, c); }
; template <bool FINAL>
; __device__ __forceinline__ void ssm_item(const Args& a, LAS unsigned char* lds, int item, int wave, int lane) {
;     ...
;     for (int st = 0; st < nsteps; ++st) {
;         bf16x8 ufn = uf; u32x2 un0 = uu0, un1 = uu1;
;         if (st + 1 < nsteps) { ufn = *(const bf16x8*)(up + (size_t)(st + 1) * 8 * DM);
;             if (FINAL) { un0 = *(const u32x2*)(ue + (size_t)(st + 1) * 8 * DM); un1 = *(const u32x2*)(ue + (size_t)(st + 1) * 8 * DM + (size_t)SEQ * DM); } }
;         f32x16 X[4];
; #pragma unroll
;         for (int k = 0; k < 4; ++k) { f32x16 z;
; #pragma unroll
;             for (int e = 0; e < 16; ++e) z[e] = 0.f;
;             X[k] = __builtin_amdgcn_mfma_f32_32x32x16_bf16(uf, bbf[k], z, 0, 0, 0); }
; #pragma unroll
;         for (int t = 0; t < 8; ++t) {
;             const f32x2 x0r = (f32x2){X[0][2 * t], X[0][2 * t + 1]}, x0i = (f32x2){X[1][2 * t], X[1][2 * t + 1]}, x1r = (f32x2){X[2][2 * t], X[2][2 * t + 1]}, x1i = (f32x2){X[3][2 * t], X[3][2 * t + 1]};
;             const f32x2 n0r = pk_fma(a0x, s0r, pk_fma(na0y, s0i, x0r)), n0i = pk_fma(a0x, s0i, pk_fma(a0y, s0r, x0i));
;             const f32x2 n1r = pk_fma(a1x, s1r, pk_fma(na1y, s1i, x1r)), n1i = pk_fma(a1x, s1i, pk_fma(a1y, s1r, x1i));
;             s0r = n0r; s0i = n0i; s1r = n1r; s1i = n1i;
.Lssm1_nopre:
	global_load_dwordx4 v[132:135], v[110:111], off
	v_lshl_add_u64 v[110:111], v[110:111], 0, s[12:13]
	global_load_dwordx4 v[144:147], v[110:111], off
	v_lshl_add_u64 v[110:111], v[110:111], 0, s[12:13]
	global_load_dwordx4 v[148:151], v[110:111], off
	v_lshl_add_u64 v[110:111], v[110:111], 0, s[12:13]
	s_mov_b32 s29, 8
	v_mov_b32_e32 v120, 0
	v_mov_b32_e32 v121, 0
	v_mov_b32_e32 v122, 0
	v_mov_b32_e32 v123, 0
	v_mov_b32_e32 v124, 0
	v_mov_b32_e32 v125, 0
	v_mov_b32_e32 v126, 0
	v_mov_b32_e32 v127, 0
.Lssm1_step:
	s_waitcnt vmcnt(3)
	v_mfma_f32_32x32x16_bf16 v[0:15], v[80:83], v[68:71], 0
	v_mfma_f32_32x32x16_bf16 v[16:31], v[80:83], v[72:75], 0
	v_mfma_f32_32x32x16_bf16 v[32:47], v[80:83], v[76:79], 0
	v_mfma_f32_32x32x16_bf16 v[48:63], v[80:83], v[64:67], 0
	s_nop 15
	global_load_dwordx4 v[80:83], v[110:111], off
	v_lshl_add_u64 v[110:111], v[110:111], 0, s[12:13]
	v_pk_fma_f32 v[0:1], v[106:107], v[122:123], v[0:1]
	v_pk_fma_f32 v[16:17], v[98:99], v[120:121], v[16:17]
	v_pk_fma_f32 v[32:33], v[108:109], v[126:127], v[32:33]
	v_pk_fma_f32 v[48:49], v[96:97], v[124:125], v[48:49]
	v_pk_fma_f32 v[0:1], v[100:101], v[120:121], v[0:1]
	v_pk_fma_f32 v[16:17], v[100:101], v[122:123], v[16:17]
	v_pk_fma_f32 v[32:33], v[102:103], v[124:125], v[32:33]
	v_pk_fma_f32 v[48:49], v[102:103], v[126:127], v[48:49]
	v_pk_fma_f32 v[2:3], v[106:107], v[16:17], v[2:3]
	v_pk_fma_f32 v[18:19], v[98:99], v[0:1], v[18:19]
	v_pk_fma_f32 v[34:35], v[108:109], v[48:49], v[34:35]
	v_pk_fma_f32 v[50:51], v[96:97], v[32:33], v[50:51]
	v_pk_fma_f32 v[2:3], v[100:101], v[0:1], v[2:3]
	v_pk_fma_f32 v[18:19], v[100:101], v[16:17], v[18:19]
	v_pk_fma_f32 v[34:35], v[102:103], v[32:33], v[34:35]
	v_pk_fma_f32 v[50:51], v[102:103], v[48:49], v[50:51]
	v_pk_fma_f32 v[4:5], v[106:107], v[18:19], v[4:5]
	v_pk_fma_f32 v[20:21], v[98:99], v[2:3], v[20:21]
	v_pk_fma_f32 v[36:37], v[108:109], v[50:51], v[36:37]
	v_pk_fma_f32 v[52:53], v[96:97], v[34:35], v[52:53]
	v_pk_fma_f32 v[4:5], v[100:101], v[2:3], v[4:5]
	v_pk_fma_f32 v[20:21], v[100:101], v[18:19], v[20:21]
	v_pk_fma_f32 v[36:37], v[102:103], v[34:35], v[36:37]
	v_pk_fma_f32 v[52:53], v[102:103], v[50:51], v[52:53]
	v_pk_fma_f32 v[6:7], v[106:107], v[20:21], v[6:7]
	v_pk_fma_f32 v[22:23], v[98:99], v[4:5], v[22:23]
	v_pk_fma_f32 v[38:39], v[108:109], v[52:53], v[38:39]
	v_pk_fma_f32 v[54:55], v[96:97], v[36:37], v[54:55]
	v_pk_fma_f32 v[6:7], v[100:101], v[4:5], v[6:7]
	v_pk_fma_f32 v[22:23], v[100:101], v[20:21], v[22:23]
	v_pk_fma_f32 v[38:39], v[102:103], v[36:37], v[38:39]
	v_pk_fma_f32 v[54:55], v[102:103], v[52:53], v[54:55]
	v_pk_fma_f32 v[8:9], v[106:107], v[22:23], v[8:9]
	v_pk_fma_f32 v[24:25], v[98:99], v[6:7], v[24:25]
	v_pk_fma_f32 v[40:41], v[108:109], v[54:55], v[40:41]
	v_pk_fma_f32 v[56:57], v[96:97], v[38:39], v[56:57]
	v_pk_fma_f32 v[8:9], v[100:101], v[6:7], v[8:9]
	v_pk_fma_f32 v[24:25], v[100:101], v[22:23], v[24:25]
	v_pk_fma_f32 v[40:41], v[102:103], v[38:39], v[40:41]
	v_pk_fma_f32 v[56:57], v[102:103], v[54:55], v[56:57]
	v_pk_fma_f32 v[10:11], v[106:107], v[24:25], v[10:11]
	v_pk_fma_f32 v[26:27], v[98:99], v[8:9], v[26:27]
	v_pk_fma_f32 v[42:43], v[108:109], v[56:57], v[42:43]
	v_pk_fma_f32 v[58:59], v[96:97], v[40:41], v[58:59]
	v_pk_fma_f32 v[10:11], v[100:101], v[8:9], v[10:11]
	v_pk_fma_f32 v[26:27], v[100:101], v[24:25], v[26:27]
	v_pk_fma_f32 v[42:43], v[102:103], v[40:41], v[42:43]
	v_pk_fma_f32 v[58:59], v[102:103], v[56:57], v[58:59]
	v_pk_fma_f32 v[12:13], v[106:107], v[26:27], v[12:13]
	v_pk_fma_f32 v[28:29], v[98:99], v[10:11], v[28:29]
	v_pk_fma_f32 v[44:45], v[108:109], v[58:59], v[44:45]
	v_pk_fma_f32 v[60:61], v[96:97], v[42:43], v[60:61]
	v_pk_fma_f32 v[12:13], v[100:101], v[10:11], v[12:13]
	v_pk_fma_f32 v[28:29], v[100:101], v[26:27], v[28:29]
	v_pk_fma_f32 v[44:45], v[102:103], v[42:43], v[44:45]
	v_pk_fma_f32 v[60:61], v[102:103], v[58:59], v[60:61]
	v_pk_fma_f32 v[14:15], v[106:107], v[28:29], v[14:15]
	v_pk_fma_f32 v[30:31], v[98:99], v[12:13], v[30:31]
	v_pk_fma_f32 v[46:47], v[108:109], v[60:61], v[46:47]
	v_pk_fma_f32 v[62:63], v[96:97], v[44:45], v[62:63]
	v_pk_fma_f32 v[120:121], v[100:101], v[12:13], v[14:15]
	v_pk_fma_f32 v[122:123], v[100:101], v[28:29], v[30:31]
	v_pk_fma_f32 v[124:125], v[102:103], v[44:45], v[46:47]
	v_pk_fma_f32 v[126:127], v[102:103], v[60:61], v[62:63]
	s_waitcnt vmcnt(3)
; __device__ __forceinline__ f32x2 pk_fma(f32x2 a, f32x2 b, f32x2 c) { return __builtin_elementwise_fma(a, b, c); }
; template <bool FINAL>
; __device__ __forceinline__ void ssm_item(const Args& a, LAS unsigned char* lds, int item, int wave, int lane) {
;     ...
;     for (int st = 0; st < nsteps; ++st) {
;         bf16x8 ufn = uf; u32x2 un0 = uu0, un1 = uu1;
;         if (st + 1 < nsteps) { ufn = *(const bf16x8*)(up + (size_t)(st + 1) * 8 * DM);
;             if (FINAL) { un0 = *(const u32x2*)(ue + (size_t)(st + 1) * 8 * DM); un1 = *(const u32x2*)(ue + (size_t)(st + 1) * 8 * DM + (size_t)SEQ * DM); } }
;         f32x16 X[4];
; #pragma unroll
;         for (int k = 0; k < 4; ++k) { f32x16 z;
; #pragma unroll
;             for (int e = 0; e < 16; ++e) z[e] = 0.f;
;             X[k] = __builtin_amdgcn_mfma_f32_32x32x16_bf16(uf, bbf[k], z, 0, 0, 0); }
; #pragma unroll
;         for (int t = 0; t < 8; ++t) {
;             const f32x2 x0r = (f32x2){X[0][2 * t], X[0][2 * t + 1]}, x0i = (f32x2){X[1][2 * t], X[1][2 * t + 1]}, x1r = (f32x2){X[2][2 * t], X[2][2 * t + 1]}, x1i = (f32x2){X[3][2 * t], X[3][2 * t + 1]};
;             const f32x2 n0r = pk_fma(a0x, s0r, pk_fma(na0y, s0i, x0r)), n0i = pk_fma(a0x, s0i, pk_fma(a0y, s0r, x0i));
;             const f32x2 n1r = pk_fma(a1x, s1r, pk_fma(na1y, s1i, x1r)), n1i = pk_fma(a1x, s1i, pk_fma(a1y, s1r, x1i));
;             s0r = n0r; s0i = n0i; s1r = n1r; s1i = n1i;
	v_mfma_f32_32x32x16_bf16 v[0:15], v[132:135], v[68:71], 0
	v_mfma_f32_32x32x16_bf16 v[16:31], v[132:135], v[72:75], 0
	v_mfma_f32_32x32x16_bf16 v[32:47], v[132:135], v[76:79], 0
	v_mfma_f32_32x32x16_bf16 v[48:63], v[132:135], v[64:67], 0
	s_nop 15
	global_load_dwordx4 v[132:135], v[110:111], off
	v_lshl_add_u64 v[110:111], v[110:111], 0, s[12:13]
	v_pk_fma_f32 v[0:1], v[106:107], v[122:123], v[0:1]
	v_pk_fma_f32 v[16:17], v[98:99], v[120:121], v[16:17]
	v_pk_fma_f32 v[32:33], v[108:109], v[126:127], v[32:33]
	v_pk_fma_f32 v[48:49], v[96:97], v[124:125], v[48:49]
	v_pk_fma_f32 v[0:1], v[100:101], v[120:121], v[0:1]
	v_pk_fma_f32 v[16:17], v[100:101], v[122:123], v[16:17]
	v_pk_fma_f32 v[32:33], v[102:103], v[124:125], v[32:33]
	v_pk_fma_f32 v[48:49], v[102:103], v[126:127], v[48:49]
	v_pk_fma_f32 v[2:3], v[106:107], v[16:17], v[2:3]
	v_pk_fma_f32 v[18:19], v[98:99], v[0:1], v[18:19]
	v_pk_fma_f32 v[34:35], v[108:109], v[48:49], v[34:35]
	v_pk_fma_f32 v[50:51], v[96:97], v[32:33], v[50:51]
	v_pk_fma_f32 v[2:3], v[100:101], v[0:1], v[2:3]
	v_pk_fma_f32 v[18:19], v[100:101], v[16:17], v[18:19]
	v_pk_fma_f32 v[34:35], v[102:103], v[32:33], v[34:35]
	v_pk_fma_f32 v[50:51], v[102:103], v[48:49], v[50:51]
	v_pk_fma_f32 v[4:5], v[106:107], v[18:19], v[4:5]
	v_pk_fma_f32 v[20:21], v[98:99], v[2:3], v[20:21]
	v_pk_fma_f32 v[36:37], v[108:109], v[50:51], v[36:37]
	v_pk_fma_f32 v[52:53], v[96:97], v[34:35], v[52:53]
	v_pk_fma_f32 v[4:5], v[100:101], v[2:3], v[4:5]
	v_pk_fma_f32 v[20:21], v[100:101], v[18:19], v[20:21]
	v_pk_fma_f32 v[36:37], v[102:103], v[34:35], v[36:37]
	v_pk_fma_f32 v[52:53], v[102:103], v[50:51], v[52:53]
	v_pk_fma_f32 v[6:7], v[106:107], v[20:21], v[6:7]
	v_pk_fma_f32 v[22:23], v[98:99], v[4:5], v[22:23]
	v_pk_fma_f32 v[38:39], v[108:109], v[52:53], v[38:39]
	v_pk_fma_f32 v[54:55], v[96:97], v[36:37], v[54:55]
	v_pk_fma_f32 v[6:7], v[100:101], v[4:5], v[6:7]
	v_pk_fma_f32 v[22:23], v[100:101], v[20:21], v[22:23]
	v_pk_fma_f32 v[38:39], v[102:103], v[36:37], v[38:39]
	v_pk_fma_f32 v[54:55], v[102:103], v[52:53], v[54:55]
	v_pk_fma_f32 v[8:9], v[106:107], v[22:23], v[8:9]
	v_pk_fma_f32 v[24:25], v[98:99], v[6:7], v[24:25]
	v_pk_fma_f32 v[40:41], v[108:109], v[54:55], v[40:41]
	v_pk_fma_f32 v[56:57], v[96:97], v[38:39], v[56:57]
	v_pk_fma_f32 v[8:9], v[100:101], v[6:7], v[8:9]
	v_pk_fma_f32 v[24:25], v[100:101], v[22:23], v[24:25]
	v_pk_fma_f32 v[40:41], v[102:103], v[38:39], v[40:41]
	v_pk_fma_f32 v[56:57], v[102:103], v[54:55], v[56:57]
	v_pk_fma_f32 v[10:11], v[106:107], v[24:25], v[10:11]
	v_pk_fma_f32 v[26:27], v[98:99], v[8:9], v[26:27]
	v_pk_fma_f32 v[42:43], v[108:109], v[56:57], v[42:43]
	v_pk_fma_f32 v[58:59], v[96:97], v[40:41], v[58:59]
	v_pk_fma_f32 v[10:11], v[100:101], v[8:9], v[10:11]
	v_pk_fma_f32 v[26:27], v[100:101], v[24:25], v[26:27]
	v_pk_fma_f32 v[42:43], v[102:103], v[40:41], v[42:43]
	v_pk_fma_f32 v[58:59], v[102:103], v[56:57], v[58:59]
	v_pk_fma_f32 v[12:13], v[106:107], v[26:27], v[12:13]
	v_pk_fma_f32 v[28:29], v[98:99], v[10:11], v[28:29]
	v_pk_fma_f32 v[44:45], v[108:109], v[58:59], v[44:45]
	v_pk_fma_f32 v[60:61], v[96:97], v[42:43], v[60:61]
	v_pk_fma_f32 v[12:13], v[100:101], v[10:11], v[12:13]
	v_pk_fma_f32 v[28:29], v[100:101], v[26:27], v[28:29]
	v_pk_fma_f32 v[44:45], v[102:103], v[42:43], v[44:45]
	v_pk_fma_f32 v[60:61], v[102:103], v[58:59], v[60:61]
	v_pk_fma_f32 v[14:15], v[106:107], v[28:29], v[14:15]
	v_pk_fma_f32 v[30:31], v[98:99], v[12:13], v[30:31]
	v_pk_fma_f32 v[46:47], v[108:109], v[60:61], v[46:47]
	v_pk_fma_f32 v[62:63], v[96:97], v[44:45], v[62:63]
	v_pk_fma_f32 v[120:121], v[100:101], v[12:13], v[14:15]
	v_pk_fma_f32 v[122:123], v[100:101], v[28:29], v[30:31]
	v_pk_fma_f32 v[124:125], v[102:103], v[44:45], v[46:47]
	v_pk_fma_f32 v[126:127], v[102:103], v[60:61], v[62:63]
	s_waitcnt vmcnt(3)
	v_mfma_f32_32x32x16_bf16 v[0:15], v[144:147], v[68:71], 0
	v_mfma_f32_32x32x16_bf16 v[16:31], v[144:147], v[72:75], 0
	v_mfma_f32_32x32x16_bf16 v[32:47], v[144:147], v[76:79], 0
	v_mfma_f32_32x32x16_bf16 v[48:63], v[144:147], v[64:67], 0
	s_nop 15
	global_load_dwordx4 v[144:147], v[110:111], off
	v_lshl_add_u64 v[110:111], v[110:111], 0, s[12:13]
	v_pk_fma_f32 v[0:1], v[106:107], v[122:123], v[0:1]
	v_pk_fma_f32 v[16:17], v[98:99], v[120:121], v[16:17]
	v_pk_fma_f32 v[32:33], v[108:109], v[126:127], v[32:33]
	v_pk_fma_f32 v[48:49], v[96:97], v[124:125], v[48:49]
	v_pk_fma_f32 v[0:1], v[100:101], v[120:121], v[0:1]
	v_pk_fma_f32 v[16:17], v[100:101], v[122:123], v[16:17]
	v_pk_fma_f32 v[32:33], v[102:103], v[124:125], v[32:33]
	v_pk_fma_f32 v[48:49], v[102:103], v[126:127], v[48:49]
	v_pk_fma_f32 v[2:3], v[106:107], v[16:17], v[2:3]
	v_pk_fma_f32 v[18:19], v[98:99], v[0:1], v[18:19]
	v_pk_fma_f32 v[34:35], v[108:109], v[48:49], v[34:35]
	v_pk_fma_f32 v[50:51], v[96:97], v[32:33], v[50:51]
	v_pk_fma_f32 v[2:3], v[100:101], v[0:1], v[2:3]
	v_pk_fma_f32 v[18:19], v[100:101], v[16:17], v[18:19]
	v_pk_fma_f32 v[34:35], v[102:103], v[32:33], v[34:35]
	v_pk_fma_f32 v[50:51], v[102:103], v[48:49], v[50:51]
	v_pk_fma_f32 v[4:5], v[106:107], v[18:19], v[4:5]
	v_pk_fma_f32 v[20:21], v[98:99], v[2:3], v[20:21]
	v_pk_fma_f32 v[36:37], v[108:109], v[50:51], v[36:37]
	v_pk_fma_f32 v[52:53], v[96:97], v[34:35], v[52:53]
	v_pk_fma_f32 v[4:5], v[100:101], v[2:3], v[4:5]
	v_pk_fma_f32 v[20:21], v[100:101], v[18:19], v[20:21]
	v_pk_fma_f32 v[36:37], v[102:103], v[34:35], v[36:37]
	v_pk_fma_f32 v[52:53], v[102:103], v[50:51], v[52:53]
	v_pk_fma_f32 v[6:7], v[106:107], v[20:21], v[6:7]
	v_pk_fma_f32 v[22:23], v[98:99], v[4:5], v[22:23]
	v_pk_fma_f32 v[38:39], v[108:109], v[52:53], v[38:39]
; __device__ __forceinline__ f32x2 pk_fma(f32x2 a, f32x2 b, f32x2 c) { return __builtin_elementwise_fma(a, b, c); }
; template <bool FINAL>
; __device__ __forceinline__ void ssm_item(const Args& a, LAS unsigned char* lds, int item, int wave, int lane) {
;     ...
;     for (int st = 0; st < nsteps; ++st) {
;         bf16x8 ufn = uf; u32x2 un0 = uu0, un1 = uu1;
;         if (st + 1 < nsteps) { ufn = *(const bf16x8*)(up + (size_t)(st + 1) * 8 * DM);
;             if (FINAL) { un0 = *(const u32x2*)(ue + (size_t)(st + 1) * 8 * DM); un1 = *(const u32x2*)(ue + (size_t)(st + 1) * 8 * DM + (size_t)SEQ * DM); } }
;         f32x16 X[4];
; #pragma unroll
;         for (int k = 0; k < 4; ++k) { f32x16 z;
; #pragma unroll
;             for (int e = 0; e < 16; ++e) z[e] = 0.f;
;             X[k] = __builtin_amdgcn_mfma_f32_32x32x16_bf16(uf, bbf[k], z, 0, 0, 0); }
; #pragma unroll
;         for (int t = 0; t < 8; ++t) {
;             const f32x2 x0r = (f32x2){X[0][2 * t], X[0][2 * t + 1]}, x0i = (f32x2){X[1][2 * t], X[1][2 * t + 1]}, x1r = (f32x2){X[2][2 * t], X[2][2 * t + 1]}, x1i = (f32x2){X[3][2 * t], X[3][2 * t + 1]};
;             const f32x2 n0r = pk_fma(a0x, s0r, pk_fma(na0y, s0i, x0r)), n0i = pk_fma(a0x, s0i, pk_fma(a0y, s0r, x0i));
;             const f32x2 n1r = pk_fma(a1x, s1r, pk_fma(na1y, s1i, x1r)), n1i = pk_fma(a1x, s1i, pk_fma(a1y, s1r, x1i));
;             s0r = n0r; s0i = n0i; s1r = n1r; s1i = n1i;
	v_pk_fma_f32 v[54:55], v[96:97], v[36:37], v[54:55]
	v_pk_fma_f32 v[6:7], v[100:101], v[4:5], v[6:7]
	v_pk_fma_f32 v[22:23], v[100:101], v[20:21], v[22:23]
	v_pk_fma_f32 v[38:39], v[102:103], v[36:37], v[38:39]
	v_pk_fma_f32 v[54:55], v[102:103], v[52:53], v[54:55]
	v_pk_fma_f32 v[8:9], v[106:107], v[22:23], v[8:9]
	v_pk_fma_f32 v[24:25], v[98:99], v[6:7], v[24:25]
	v_pk_fma_f32 v[40:41], v[108:109], v[54:55], v[40:41]
	v_pk_fma_f32 v[56:57], v[96:97], v[38:39], v[56:57]
	v_pk_fma_f32 v[8:9], v[100:101], v[6:7], v[8:9]
	v_pk_fma_f32 v[24:25], v[100:101], v[22:23], v[24:25]
	v_pk_fma_f32 v[40:41], v[102:103], v[38:39], v[40:41]
	v_pk_fma_f32 v[56:57], v[102:103], v[54:55], v[56:57]
	v_pk_fma_f32 v[10:11], v[106:107], v[24:25], v[10:11]
	v_pk_fma_f32 v[26:27], v[98:99], v[8:9], v[26:27]
	v_pk_fma_f32 v[42:43], v[108:109], v[56:57], v[42:43]
	v_pk_fma_f32 v[58:59], v[96:97], v[40:41], v[58:59]
	v_pk_fma_f32 v[10:11], v[100:101], v[8:9], v[10:11]
	v_pk_fma_f32 v[26:27], v[100:101], v[24:25], v[26:27]
	v_pk_fma_f32 v[42:43], v[102:103], v[40:41], v[42:43]
	v_pk_fma_f32 v[58:59], v[102:103], v[56:57], v[58:59]
	v_pk_fma_f32 v[12:13], v[106:107], v[26:27], v[12:13]
	v_pk_fma_f32 v[28:29], v[98:99], v[10:11], v[28:29]
	v_pk_fma_f32 v[44:45], v[108:109], v[58:59], v[44:45]
	v_pk_fma_f32 v[60:61], v[96:97], v[42:43], v[60:61]
	v_pk_fma_f32 v[12:13], v[100:101], v[10:11], v[12:13]
	v_pk_fma_f32 v[28:29], v[100:101], v[26:27], v[28:29]
	v_pk_fma_f32 v[44:45], v[102:103], v[42:43], v[44:45]
	v_pk_fma_f32 v[60:61], v[102:103], v[58:59], v[60:61]
	v_pk_fma_f32 v[14:15], v[106:107], v[28:29], v[14:15]
	v_pk_fma_f32 v[30:31], v[98:99], v[12:13], v[30:31]
	v_pk_fma_f32 v[46:47], v[108:109], v[60:61], v[46:47]
	v_pk_fma_f32 v[62:63], v[96:97], v[44:45], v[62:63]
	v_pk_fma_f32 v[120:121], v[100:101], v[12:13], v[14:15]
	v_pk_fma_f32 v[122:123], v[100:101], v[28:29], v[30:31]
	v_pk_fma_f32 v[124:125], v[102:103], v[44:45], v[46:47]
	v_pk_fma_f32 v[126:127], v[102:103], v[60:61], v[62:63]
	s_waitcnt vmcnt(3)
	v_mfma_f32_32x32x16_bf16 v[0:15], v[148:151], v[68:71], 0
	v_mfma_f32_32x32x16_bf16 v[16:31], v[148:151], v[72:75], 0
	v_mfma_f32_32x32x16_bf16 v[32:47], v[148:151], v[76:79], 0
	v_mfma_f32_32x32x16_bf16 v[48:63], v[148:151], v[64:67], 0
	s_add_i32 s29, s29, -1
	s_nop 15
	global_load_dwordx4 v[148:151], v[110:111], off
	v_lshl_add_u64 v[110:111], v[110:111], 0, s[12:13]
	v_pk_fma_f32 v[0:1], v[106:107], v[122:123], v[0:1]
	v_pk_fma_f32 v[16:17], v[98:99], v[120:121], v[16:17]
	v_pk_fma_f32 v[32:33], v[108:109], v[126:127], v[32:33]
	v_pk_fma_f32 v[48:49], v[96:97], v[124:125], v[48:49]
	v_pk_fma_f32 v[0:1], v[100:101], v[120:121], v[0:1]
	v_pk_fma_f32 v[16:17], v[100:101], v[122:123], v[16:17]
	v_pk_fma_f32 v[32:33], v[102:103], v[124:125], v[32:33]
	v_pk_fma_f32 v[48:49], v[102:103], v[126:127], v[48:49]
	v_pk_fma_f32 v[2:3], v[106:107], v[16:17], v[2:3]
	v_pk_fma_f32 v[18:19], v[98:99], v[0:1], v[18:19]
	v_pk_fma_f32 v[34:35], v[108:109], v[48:49], v[34:35]
	v_pk_fma_f32 v[50:51], v[96:97], v[32:33], v[50:51]
	v_pk_fma_f32 v[2:3], v[100:101], v[0:1], v[2:3]
	v_pk_fma_f32 v[18:19], v[100:101], v[16:17], v[18:19]
	v_pk_fma_f32 v[34:35], v[102:103], v[32:33], v[34:35]
	v_pk_fma_f32 v[50:51], v[102:103], v[48:49], v[50:51]
	v_pk_fma_f32 v[4:5], v[106:107], v[18:19], v[4:5]
	v_pk_fma_f32 v[20:21], v[98:99], v[2:3], v[20:21]
	v_pk_fma_f32 v[36:37], v[108:109], v[50:51], v[36:37]
	v_pk_fma_f32 v[52:53], v[96:97], v[34:35], v[52:53]
	v_pk_fma_f32 v[4:5], v[100:101], v[2:3], v[4:5]
	v_pk_fma_f32 v[20:21], v[100:101], v[18:19], v[20:21]
	v_pk_fma_f32 v[36:37], v[102:103], v[34:35], v[36:37]
	v_pk_fma_f32 v[52:53], v[102:103], v[50:51], v[52:53]
	v_pk_fma_f32 v[6:7], v[106:107], v[20:21], v[6:7]
	v_pk_fma_f32 v[22:23], v[98:99], v[4:5], v[22:23]
	v_pk_fma_f32 v[38:39], v[108:109], v[52:53], v[38:39]
	v_pk_fma_f32 v[54:55], v[96:97], v[36:37], v[54:55]
	v_pk_fma_f32 v[6:7], v[100:101], v[4:5], v[6:7]
	v_pk_fma_f32 v[22:23], v[100:101], v[20:21], v[22:23]
	v_pk_fma_f32 v[38:39], v[102:103], v[36:37], v[38:39]
	v_pk_fma_f32 v[54:55], v[102:103], v[52:53], v[54:55]
	v_pk_fma_f32 v[8:9], v[106:107], v[22:23], v[8:9]
	v_pk_fma_f32 v[24:25], v[98:99], v[6:7], v[24:25]
	v_pk_fma_f32 v[40:41], v[108:109], v[54:55], v[40:41]
	v_pk_fma_f32 v[56:57], v[96:97], v[38:39], v[56:57]
	v_pk_fma_f32 v[8:9], v[100:101], v[6:7], v[8:9]
	v_pk_fma_f32 v[24:25], v[100:101], v[22:23], v[24:25]
	v_pk_fma_f32 v[40:41], v[102:103], v[38:39], v[40:41]
	v_pk_fma_f32 v[56:57], v[102:103], v[54:55], v[56:57]
	v_pk_fma_f32 v[10:11], v[106:107], v[24:25], v[10:11]
	v_pk_fma_f32 v[26:27], v[98:99], v[8:9], v[26:27]
	v_pk_fma_f32 v[42:43], v[108:109], v[56:57], v[42:43]
	v_pk_fma_f32 v[58:59], v[96:97], v[40:41], v[58:59]
	v_pk_fma_f32 v[10:11], v[100:101], v[8:9], v[10:11]
	v_pk_fma_f32 v[26:27], v[100:101], v[24:25], v[26:27]
	v_pk_fma_f32 v[42:43], v[102:103], v[40:41], v[42:43]
	v_pk_fma_f32 v[58:59], v[102:103], v[56:57], v[58:59]
	v_pk_fma_f32 v[12:13], v[106:107], v[26:27], v[12:13]
	v_pk_fma_f32 v[28:29], v[98:99], v[10:11], v[28:29]
	v_pk_fma_f32 v[44:45], v[108:109], v[58:59], v[44:45]
	v_pk_fma_f32 v[60:61], v[96:97], v[42:43], v[60:61]
	v_pk_fma_f32 v[12:13], v[100:101], v[10:11], v[12:13]
	v_pk_fma_f32 v[28:29], v[100:101], v[26:27], v[28:29]
	v_pk_fma_f32 v[44:45], v[102:103], v[42:43], v[44:45]
	v_pk_fma_f32 v[60:61], v[102:103], v[58:59], v[60:61]
	v_pk_fma_f32 v[14:15], v[106:107], v[28:29], v[14:15]
	v_pk_fma_f32 v[30:31], v[98:99], v[12:13], v[30:31]
	v_pk_fma_f32 v[46:47], v[108:109], v[60:61], v[46:47]
	v_pk_fma_f32 v[62:63], v[96:97], v[44:45], v[62:63]
	v_pk_fma_f32 v[120:121], v[100:101], v[12:13], v[14:15]
	v_pk_fma_f32 v[122:123], v[100:101], v[28:29], v[30:31]
	v_pk_fma_f32 v[124:125], v[102:103], v[44:45], v[46:47]
	v_pk_fma_f32 v[126:127], v[102:103], v[60:61], v[62:63]
	s_cmp_lg_u32 s29, 0
	s_cbranch_scc1 .Lssm1_step
	v_mov_b64_e32 v[0:1], v[120:121]
	v_mov_b64_e32 v[4:5], v[122:123]
	v_mov_b64_e32 v[2:3], v[124:125]
	v_mov_b64_e32 v[6:7], v[126:127]
	s_mov_b64 s[16:17], -1
	s_and_b64 vcc, exec, s[14:15]
	s_cbranch_vccnz .LBB0_271
	s_andn2_b64 vcc, exec, s[16:17]
	s_cbranch_vccnz .LBB0_264
	s_branch .LBB0_272
